# adds: GDN stage no longer drains readout stores after barrier F (wave 7 consumes its second-group loads before its readout; vmcnt drain kept for stage 0)
# speedup vs baseline: 1.0031x; 1.0026x over previous
.LBB0_967:
	v_or_b32_e32 v1, s65, v137
	v_lshlrev_b32_e32 v0, 1, v143
	v_mul_lo_u32 v1, v1, s10
	v_add3_u32 v3, 0, v1, v0
	v_mul_u32_u24_e32 v1, 40, v137
	s_add_i32 s0, 0, 0x1f400
	v_lshlrev_b32_e32 v1, 1, v1
	s_waitcnt lgkmcnt(0)
	s_barrier
	s_cmp_lg_u32 s3, 0
	s_cbranch_scc0 .Lgdn_drain
	s_waitcnt lgkmcnt(0)
	s_branch .Lgdn_drained
.Lgdn_drain:
	s_waitcnt vmcnt(0) lgkmcnt(0)
.Lgdn_drained:
	v_add3_u32 v88, s0, v0, v1
	ds_read_b128 v[68:71], v88
	ds_read_b128 v[72:75], v3 offset:55296
	s_waitcnt lgkmcnt(0)
	v_mfma_f32_16x16x32_bf16 v[68:71], v[68:71], v[72:75], 0
	ds_read_b128 v[72:75], v3 offset:34816
	v_add3_u32 v89, s47, v0, v1
	ds_read_b128 v[76:79], v89
	s_waitcnt lgkmcnt(0)
	v_mfma_f32_16x16x32_bf16 v[72:75], v[72:75], v[76:79], 0
	v_add_u32_e32 v108, 0, v139
	v_add_u32_e32 v107, s76, v140
	v_add_u32_e32 v101, s85, v139
	s_nop 4
	v_xor_b32_e32 v0, 0x80000000, v73
	v_xor_b32_e32 v1, 0x80000000, v72
	v_cvt_pk_bf16_f32 v0, v1, v0
	v_xor_b32_e32 v1, 0x80000000, v74
	v_xor_b32_e32 v72, 0x80000000, v75
	v_cvt_pk_bf16_f32 v1, v1, v72
	v_mul_u32_u24_e32 v72, 0x110, v137
	v_add3_u32 v92, s67, v139, v72
	ds_write_b64 v92, v[0:1]
	ds_read_b128 v[72:75], v88 offset:1280
	ds_read_b128 v[76:79], v3 offset:55328
	s_waitcnt lgkmcnt(0)
	v_mfma_f32_16x16x32_bf16 v[80:83], v[72:75], v[76:79], 0
	ds_read_b128 v[72:75], v3 offset:34848
	ds_read_b128 v[76:79], v89 offset:1280
	v_mad_u32_u24 v103, v137, s10, v108
	v_or_b32_e32 v110, 16, v137
	s_waitcnt lgkmcnt(0)
	v_mfma_f32_16x16x32_bf16 v[72:75], v[72:75], v[76:79], 0
	v_mad_u32_u24 v104, v110, s10, v108
	v_or_b32_e32 v109, 32, v137
	v_or_b32_e32 v100, 48, v137
	s_nop 4
	v_xor_b32_e32 v0, 0x80000000, v73
	v_xor_b32_e32 v1, 0x80000000, v72
	v_cvt_pk_bf16_f32 v0, v1, v0
	v_xor_b32_e32 v1, 0x80000000, v74
	v_xor_b32_e32 v72, 0x80000000, v75
	v_cvt_pk_bf16_f32 v1, v1, v72
	ds_write_b64 v92, v[0:1] offset:4352
	ds_read_b128 v[72:75], v88 offset:2560
	ds_read_b128 v[76:79], v3 offset:55360
	s_waitcnt lgkmcnt(0)
	v_mfma_f32_16x16x32_bf16 v[76:79], v[72:75], v[76:79], 0
	ds_read_b128 v[72:75], v3 offset:34880
	ds_read_b128 v[84:87], v89 offset:2560
	s_add_i32 s56, s56, 1
	s_add_i32 s3, s3, 64
	s_waitcnt lgkmcnt(0)
	v_mfma_f32_16x16x32_bf16 v[72:75], v[72:75], v[84:87], 0
	s_add_i32 s96, s96, 1
	s_cmpk_eq_i32 s3, 0x900
	s_nop 5
	v_xor_b32_e32 v0, 0x80000000, v73
	v_xor_b32_e32 v1, 0x80000000, v72
	v_cvt_pk_bf16_f32 v0, v1, v0
	v_xor_b32_e32 v1, 0x80000000, v74
	v_xor_b32_e32 v72, 0x80000000, v75
	v_cvt_pk_bf16_f32 v1, v1, v72
	ds_write_b64 v92, v[0:1] offset:8704
	ds_read_b128 v[72:75], v88 offset:3840
	ds_read_b128 v[84:87], v3 offset:55392
	s_waitcnt lgkmcnt(0)
	v_mfma_f32_16x16x32_bf16 v[72:75], v[72:75], v[84:87], 0
	ds_read_b128 v[84:87], v3 offset:34912
	ds_read_b128 v[88:91], v89 offset:3840
	s_waitcnt lgkmcnt(0)
	v_mfma_f32_16x16x32_bf16 v[84:87], v[84:87], v[88:91], 0
	v_cvt_pk_bf16_f32 v88, v40, v41
	v_cvt_pk_bf16_f32 v89, v42, v43
	s_nop 5
	v_xor_b32_e32 v0, 0x80000000, v85
	v_xor_b32_e32 v1, 0x80000000, v84
	v_cvt_pk_bf16_f32 v0, v1, v0
	v_xor_b32_e32 v1, 0x80000000, v86
	v_xor_b32_e32 v3, 0x80000000, v87
	v_cvt_pk_bf16_f32 v1, v1, v3
	ds_write_b64 v92, v[0:1] offset:13056
	v_add_u32_e32 v0, 0, v140
	s_waitcnt lgkmcnt(0)
	v_add_u32_e32 v106, 0x24a80, v0
	v_add_u32_e32 v102, 0x24b80, v0
	v_mul_u32_u24_e32 v0, 0x88, v137
	v_lshl_add_u32 v0, v0, 1, v108
	s_waitcnt lgkmcnt(0)
	s_barrier
	v_mov_b32_e32 v218, 0
	v_mov_b32_e32 v219, 0
	v_mov_b32_e32 v234, 0
	v_mov_b32_e32 v235, 0
	v_mov_b32_e32 v242, 0
	v_mov_b32_e32 v243, 0
	v_mov_b32_e32 v246, 0
	v_mov_b32_e32 v247, 0
	v_mov_b32_e32 v250, s76
	ds_read_b128 v[236:239], v250 offset:768
	ds_read_b64 v[154:155], v0
	ds_read_b64 v[156:157], v0 offset:32
	ds_read_b64 v[170:171], v0 offset:17408
	ds_read_b64 v[172:173], v0 offset:17440
	ds_read_b64 v[158:159], v0 offset:64
	ds_read_b64 v[160:161], v0 offset:96
	ds_read_b64 v[174:175], v0 offset:17472
	ds_read_b64 v[176:177], v0 offset:17504
	v_mad_u32_u24 v252, v137, s84, v101
	v_lshlrev_b32_e32 v92, 1, v137
	v_mul_u32_u24_e32 v93, 0x440, v138
	v_add3_u32 v253, s89, v92, v93
	v_cvt_pk_bf16_f32 v186, v36, v37
	v_cvt_pk_bf16_f32 v187, v38, v39
	v_cvt_pk_bf16_f32 v188, v40, v41
	v_cvt_pk_bf16_f32 v189, v42, v43
	ds_read_b64 v[162:163], v0 offset:128
	ds_read_b64 v[164:165], v0 offset:160
	ds_read_b64 v[178:179], v0 offset:17536
	ds_read_b64 v[180:181], v0 offset:17568
	s_waitcnt lgkmcnt(8)
	v_mfma_f32_16x16x32_bf16 v[68:71], v[154:157], v[186:189], v[68:71]
	v_mfma_f32_16x16x32_bf16 v[84:87], v[170:173], v[186:189], 0
	v_cvt_pk_bf16_f32 v190, v44, v45
	v_cvt_pk_bf16_f32 v191, v46, v47
	v_cvt_pk_bf16_f32 v192, v48, v49
	v_cvt_pk_bf16_f32 v193, v50, v51
	ds_read_b64 v[166:167], v0 offset:192
	ds_read_b64 v[168:169], v0 offset:224
	ds_read_b64 v[182:183], v0 offset:17600
	ds_read_b64 v[184:185], v0 offset:17632
	s_waitcnt lgkmcnt(8)
	v_mfma_f32_16x16x32_bf16 v[68:71], v[158:161], v[190:193], v[68:71]
	v_mfma_f32_16x16x32_bf16 v[84:87], v[174:177], v[190:193], v[84:87]
	v_cvt_pk_bf16_f32 v194, v52, v53
	v_cvt_pk_bf16_f32 v195, v54, v55
	v_cvt_pk_bf16_f32 v196, v56, v57
	v_cvt_pk_bf16_f32 v197, v58, v59
	ds_read_b64 v[202:203], v103 offset:34816
	ds_read_b64 v[204:205], v104 offset:34816
	ds_read_b64 v[206:207], v104 offset:37376
	ds_read_b64 v[208:209], v104 offset:39936
	s_waitcnt lgkmcnt(8)
	v_mfma_f32_16x16x32_bf16 v[68:71], v[162:165], v[194:197], v[68:71]
	v_mfma_f32_16x16x32_bf16 v[84:87], v[178:181], v[194:197], v[84:87]
	v_cvt_pk_bf16_f32 v198, v60, v61
	v_cvt_pk_bf16_f32 v199, v62, v63
	v_cvt_pk_bf16_f32 v200, v64, v65
	v_cvt_pk_bf16_f32 v201, v66, v67
	ds_read_b64 v[210:211], v103 offset:45056
	ds_read_b64 v[212:213], v103 offset:47616
	ds_read_b64 v[214:215], v103 offset:50176
	ds_read_b64 v[216:217], v103 offset:52736
	s_waitcnt lgkmcnt(8)
	v_mfma_f32_16x16x32_bf16 v[68:71], v[166:169], v[198:201], v[68:71]
	v_mfma_f32_16x16x32_bf16 v[84:87], v[182:185], v[198:201], v[84:87]
	ds_read_b128 v[220:223], v106
	ds_read_b128 v[224:227], v107 offset:512
	ds_read_b128 v[228:231], v102
	ds_read_b64 v[232:233], v252
	v_pk_mul_f32 v[36:37], v[36:37], v[236:237] op_sel_hi:[1,0]
	v_pk_mul_f32 v[38:39], v[38:39], v[236:237] op_sel_hi:[1,0]
	v_pk_mul_f32 v[40:41], v[40:41], v[236:237] op_sel_hi:[1,0]
	v_pk_mul_f32 v[42:43], v[42:43], v[236:237] op_sel_hi:[1,0]
	v_pk_mul_f32 v[44:45], v[44:45], v[236:237] op_sel_hi:[1,0]
	v_pk_mul_f32 v[46:47], v[46:47], v[236:237] op_sel_hi:[1,0]
	v_pk_mul_f32 v[48:49], v[48:49], v[236:237] op_sel_hi:[1,0]
	v_pk_mul_f32 v[50:51], v[50:51], v[236:237] op_sel_hi:[1,0]
	v_pk_mul_f32 v[52:53], v[52:53], v[236:237] op_sel_hi:[1,0]
	v_pk_mul_f32 v[54:55], v[54:55], v[236:237] op_sel_hi:[1,0]
	v_pk_mul_f32 v[56:57], v[56:57], v[236:237] op_sel_hi:[1,0]
	v_pk_mul_f32 v[58:59], v[58:59], v[236:237] op_sel_hi:[1,0]
	v_pk_mul_f32 v[60:61], v[60:61], v[236:237] op_sel_hi:[1,0]
	v_pk_mul_f32 v[62:63], v[62:63], v[236:237] op_sel_hi:[1,0]
	v_pk_mul_f32 v[64:65], v[64:65], v[236:237] op_sel_hi:[1,0]
	v_pk_mul_f32 v[66:67], v[66:67], v[236:237] op_sel_hi:[1,0]
	s_waitcnt lgkmcnt(2)
	v_cvt_pk_bf16_f32 v240, v68, v69
	v_cvt_pk_bf16_f32 v241, v70, v71
	v_pk_mul_f32 v[88:89], v[68:69], v[220:221]
	v_pk_mul_f32 v[90:91], v[70:71], v[222:223]
	v_cvt_pk_bf16_f32 v244, v88, v89
	v_cvt_pk_bf16_f32 v245, v90, v91
	v_pk_mul_f32 v[84:85], v[84:85], v[224:225]
	v_pk_mul_f32 v[86:87], v[86:87], v[226:227]
	s_waitcnt lgkmcnt(0)
	v_mfma_f32_16x16x32_bf16 v[36:39], v[202:205], v[244:247], v[36:39]
	v_mfma_f32_16x16x32_bf16 v[40:43], v[204:207], v[244:247], v[40:43]
	v_mfma_f32_16x16x32_bf16 v[84:87], v[232:235], v[240:243], v[84:87]
	v_add_u32_e32 v250, 4352, v0
	v_mfma_f32_16x16x32_bf16 v[44:47], v[206:209], v[244:247], v[44:47]
	v_mfma_f32_16x16x32_bf16 v[48:51], v[208:211], v[244:247], v[48:51]
	v_mfma_f32_16x16x32_bf16 v[52:55], v[210:213], v[244:247], v[52:55]
	v_mfma_f32_16x16x32_bf16 v[56:59], v[212:215], v[244:247], v[56:59]
	v_mfma_f32_16x16x32_bf16 v[60:63], v[214:217], v[244:247], v[60:63]
	v_mfma_f32_16x16x32_bf16 v[64:67], v[216:219], v[244:247], v[64:67]
	ds_read_b64 v[154:155], v250
	ds_read_b64 v[156:157], v250 offset:32
	ds_read_b64 v[170:171], v250 offset:17408
	ds_read_b64 v[172:173], v250 offset:17440
	ds_read_b64 v[158:159], v250 offset:64
	ds_read_b64 v[160:161], v250 offset:96
	ds_read_b64 v[174:175], v250 offset:17472
	ds_read_b64 v[176:177], v250 offset:17504
	v_pk_mul_f32 v[84:85], v[84:85], v[228:229]
	v_pk_mul_f32 v[86:87], v[86:87], v[230:231]
	v_cvt_pk_bf16_f32 v88, v84, v85
	v_cvt_pk_bf16_f32 v90, v86, v87
	v_lshrrev_b32_e32 v89, 16, v88
	v_lshrrev_b32_e32 v91, 16, v90
	ds_write_b16 v253, v88
	ds_write_b16 v253, v89 offset:272
	ds_write_b16 v253, v90 offset:544
	ds_write_b16 v253, v91 offset:816
	v_cvt_pk_bf16_f32 v186, v36, v37
	v_cvt_pk_bf16_f32 v187, v38, v39
	v_cvt_pk_bf16_f32 v188, v40, v41
	v_cvt_pk_bf16_f32 v189, v42, v43
	s_waitcnt lgkmcnt(8)
	ds_read_b64 v[162:163], v250 offset:128
	ds_read_b64 v[164:165], v250 offset:160
	ds_read_b64 v[178:179], v250 offset:17536
	ds_read_b64 v[180:181], v250 offset:17568
	s_waitcnt lgkmcnt(8)
	v_mfma_f32_16x16x32_bf16 v[80:83], v[154:157], v[186:189], v[80:83]
	v_mfma_f32_16x16x32_bf16 v[84:87], v[170:173], v[186:189], 0
	v_cvt_pk_bf16_f32 v190, v44, v45
	v_cvt_pk_bf16_f32 v191, v46, v47
	v_cvt_pk_bf16_f32 v192, v48, v49
	v_cvt_pk_bf16_f32 v193, v50, v51
	ds_read_b64 v[166:167], v250 offset:192
	ds_read_b64 v[168:169], v250 offset:224
	ds_read_b64 v[182:183], v250 offset:17600
	ds_read_b64 v[184:185], v250 offset:17632
	s_waitcnt lgkmcnt(8)
	v_mfma_f32_16x16x32_bf16 v[80:83], v[158:161], v[190:193], v[80:83]
	v_mfma_f32_16x16x32_bf16 v[84:87], v[174:177], v[190:193], v[84:87]
	v_cvt_pk_bf16_f32 v194, v52, v53
	v_cvt_pk_bf16_f32 v195, v54, v55
	v_cvt_pk_bf16_f32 v196, v56, v57
	v_cvt_pk_bf16_f32 v197, v58, v59
	ds_read_b64 v[202:203], v103 offset:34848
	ds_read_b64 v[204:205], v104 offset:34848
	ds_read_b64 v[206:207], v104 offset:37408
	ds_read_b64 v[208:209], v104 offset:39968
	s_waitcnt lgkmcnt(8)
	v_mfma_f32_16x16x32_bf16 v[80:83], v[162:165], v[194:197], v[80:83]
	v_mfma_f32_16x16x32_bf16 v[84:87], v[178:181], v[194:197], v[84:87]
	v_cvt_pk_bf16_f32 v198, v60, v61
	v_cvt_pk_bf16_f32 v199, v62, v63
	v_cvt_pk_bf16_f32 v200, v64, v65
	v_cvt_pk_bf16_f32 v201, v66, v67
	ds_read_b64 v[210:211], v103 offset:45088
	ds_read_b64 v[212:213], v103 offset:47648
	ds_read_b64 v[214:215], v103 offset:50208
	ds_read_b64 v[216:217], v103 offset:52768
	s_waitcnt lgkmcnt(8)
	v_mfma_f32_16x16x32_bf16 v[80:83], v[166:169], v[198:201], v[80:83]
	v_mfma_f32_16x16x32_bf16 v[84:87], v[182:185], v[198:201], v[84:87]
	ds_read_b128 v[220:223], v106 offset:64
	ds_read_b128 v[224:227], v107 offset:576
	ds_read_b128 v[228:231], v102 offset:64
	ds_read_b64 v[232:233], v252 offset:1280
	v_pk_mul_f32 v[36:37], v[36:37], v[236:237] op_sel:[0,1]
	v_pk_mul_f32 v[38:39], v[38:39], v[236:237] op_sel:[0,1]
	v_pk_mul_f32 v[40:41], v[40:41], v[236:237] op_sel:[0,1]
	v_pk_mul_f32 v[42:43], v[42:43], v[236:237] op_sel:[0,1]
	v_pk_mul_f32 v[44:45], v[44:45], v[236:237] op_sel:[0,1]
	v_pk_mul_f32 v[46:47], v[46:47], v[236:237] op_sel:[0,1]
	v_pk_mul_f32 v[48:49], v[48:49], v[236:237] op_sel:[0,1]
	v_pk_mul_f32 v[50:51], v[50:51], v[236:237] op_sel:[0,1]
	v_pk_mul_f32 v[52:53], v[52:53], v[236:237] op_sel:[0,1]
	v_pk_mul_f32 v[54:55], v[54:55], v[236:237] op_sel:[0,1]
	v_pk_mul_f32 v[56:57], v[56:57], v[236:237] op_sel:[0,1]
	v_pk_mul_f32 v[58:59], v[58:59], v[236:237] op_sel:[0,1]
	v_pk_mul_f32 v[60:61], v[60:61], v[236:237] op_sel:[0,1]
	v_pk_mul_f32 v[62:63], v[62:63], v[236:237] op_sel:[0,1]
	v_pk_mul_f32 v[64:65], v[64:65], v[236:237] op_sel:[0,1]
	v_pk_mul_f32 v[66:67], v[66:67], v[236:237] op_sel:[0,1]
	s_waitcnt lgkmcnt(2)
	v_cvt_pk_bf16_f32 v240, v80, v81
	v_cvt_pk_bf16_f32 v241, v82, v83
	v_pk_mul_f32 v[88:89], v[80:81], v[220:221]
	v_pk_mul_f32 v[90:91], v[82:83], v[222:223]
	v_cvt_pk_bf16_f32 v244, v88, v89
	v_cvt_pk_bf16_f32 v245, v90, v91
	v_pk_mul_f32 v[84:85], v[84:85], v[224:225]
	v_pk_mul_f32 v[86:87], v[86:87], v[226:227]
	s_waitcnt lgkmcnt(0)
	v_mfma_f32_16x16x32_bf16 v[36:39], v[202:205], v[244:247], v[36:39]
	v_mfma_f32_16x16x32_bf16 v[40:43], v[204:207], v[244:247], v[40:43]
	v_mfma_f32_16x16x32_bf16 v[84:87], v[232:235], v[240:243], v[84:87]
	v_add_u32_e32 v250, 8704, v0
	v_mfma_f32_16x16x32_bf16 v[44:47], v[206:209], v[244:247], v[44:47]
	v_mfma_f32_16x16x32_bf16 v[48:51], v[208:211], v[244:247], v[48:51]
	v_mfma_f32_16x16x32_bf16 v[52:55], v[210:213], v[244:247], v[52:55]
	v_mfma_f32_16x16x32_bf16 v[56:59], v[212:215], v[244:247], v[56:59]
	v_mfma_f32_16x16x32_bf16 v[60:63], v[214:217], v[244:247], v[60:63]
	v_mfma_f32_16x16x32_bf16 v[64:67], v[216:219], v[244:247], v[64:67]
	ds_read_b64 v[154:155], v250
	ds_read_b64 v[156:157], v250 offset:32
	ds_read_b64 v[170:171], v250 offset:17408
	ds_read_b64 v[172:173], v250 offset:17440
	ds_read_b64 v[158:159], v250 offset:64
	ds_read_b64 v[160:161], v250 offset:96
	ds_read_b64 v[174:175], v250 offset:17472
	ds_read_b64 v[176:177], v250 offset:17504
	v_pk_mul_f32 v[84:85], v[84:85], v[228:229]
	v_pk_mul_f32 v[86:87], v[86:87], v[230:231]
	v_cvt_pk_bf16_f32 v88, v84, v85
	v_cvt_pk_bf16_f32 v90, v86, v87
	v_lshrrev_b32_e32 v89, 16, v88
	v_lshrrev_b32_e32 v91, 16, v90
	ds_write_b16 v253, v88 offset:4352
	ds_write_b16 v253, v89 offset:4624
	ds_write_b16 v253, v90 offset:4896
	ds_write_b16 v253, v91 offset:5168
	v_cvt_pk_bf16_f32 v186, v36, v37
	v_cvt_pk_bf16_f32 v187, v38, v39
	v_cvt_pk_bf16_f32 v188, v40, v41
	v_cvt_pk_bf16_f32 v189, v42, v43
	s_waitcnt lgkmcnt(8)
	ds_read_b64 v[162:163], v250 offset:128
	ds_read_b64 v[164:165], v250 offset:160
	ds_read_b64 v[178:179], v250 offset:17536
	ds_read_b64 v[180:181], v250 offset:17568
	s_waitcnt lgkmcnt(8)
	v_mfma_f32_16x16x32_bf16 v[76:79], v[154:157], v[186:189], v[76:79]
	v_mfma_f32_16x16x32_bf16 v[84:87], v[170:173], v[186:189], 0
	v_cvt_pk_bf16_f32 v190, v44, v45
	v_cvt_pk_bf16_f32 v191, v46, v47
	v_cvt_pk_bf16_f32 v192, v48, v49
	v_cvt_pk_bf16_f32 v193, v50, v51
	ds_read_b64 v[166:167], v250 offset:192
	ds_read_b64 v[168:169], v250 offset:224
	ds_read_b64 v[182:183], v250 offset:17600
	ds_read_b64 v[184:185], v250 offset:17632
	s_waitcnt lgkmcnt(8)
	v_mfma_f32_16x16x32_bf16 v[76:79], v[158:161], v[190:193], v[76:79]
	v_mfma_f32_16x16x32_bf16 v[84:87], v[174:177], v[190:193], v[84:87]
	v_cvt_pk_bf16_f32 v194, v52, v53
	v_cvt_pk_bf16_f32 v195, v54, v55
	v_cvt_pk_bf16_f32 v196, v56, v57
	v_cvt_pk_bf16_f32 v197, v58, v59
	ds_read_b64 v[202:203], v103 offset:34880
	ds_read_b64 v[204:205], v104 offset:34880
	ds_read_b64 v[206:207], v104 offset:37440
	ds_read_b64 v[208:209], v104 offset:40000
	s_waitcnt lgkmcnt(8)
	v_mfma_f32_16x16x32_bf16 v[76:79], v[162:165], v[194:197], v[76:79]
	v_mfma_f32_16x16x32_bf16 v[84:87], v[178:181], v[194:197], v[84:87]
	v_cvt_pk_bf16_f32 v198, v60, v61
	v_cvt_pk_bf16_f32 v199, v62, v63
	v_cvt_pk_bf16_f32 v200, v64, v65
	v_cvt_pk_bf16_f32 v201, v66, v67
	ds_read_b64 v[210:211], v103 offset:45120
	ds_read_b64 v[212:213], v103 offset:47680
	ds_read_b64 v[214:215], v103 offset:50240
	ds_read_b64 v[216:217], v103 offset:52800
	s_waitcnt lgkmcnt(8)
	v_mfma_f32_16x16x32_bf16 v[76:79], v[166:169], v[198:201], v[76:79]
	v_mfma_f32_16x16x32_bf16 v[84:87], v[182:185], v[198:201], v[84:87]
	ds_read_b128 v[220:223], v106 offset:128
	ds_read_b128 v[224:227], v107 offset:640
	ds_read_b128 v[228:231], v102 offset:128
	ds_read_b64 v[232:233], v252 offset:2560
	v_pk_mul_f32 v[36:37], v[36:37], v[238:239] op_sel_hi:[1,0]
	v_pk_mul_f32 v[38:39], v[38:39], v[238:239] op_sel_hi:[1,0]
	v_pk_mul_f32 v[40:41], v[40:41], v[238:239] op_sel_hi:[1,0]
	v_pk_mul_f32 v[42:43], v[42:43], v[238:239] op_sel_hi:[1,0]
	v_pk_mul_f32 v[44:45], v[44:45], v[238:239] op_sel_hi:[1,0]
	v_pk_mul_f32 v[46:47], v[46:47], v[238:239] op_sel_hi:[1,0]
	v_pk_mul_f32 v[48:49], v[48:49], v[238:239] op_sel_hi:[1,0]
	v_pk_mul_f32 v[50:51], v[50:51], v[238:239] op_sel_hi:[1,0]
	v_pk_mul_f32 v[52:53], v[52:53], v[238:239] op_sel_hi:[1,0]
	v_pk_mul_f32 v[54:55], v[54:55], v[238:239] op_sel_hi:[1,0]
	v_pk_mul_f32 v[56:57], v[56:57], v[238:239] op_sel_hi:[1,0]
	v_pk_mul_f32 v[58:59], v[58:59], v[238:239] op_sel_hi:[1,0]
	v_pk_mul_f32 v[60:61], v[60:61], v[238:239] op_sel_hi:[1,0]
	v_pk_mul_f32 v[62:63], v[62:63], v[238:239] op_sel_hi:[1,0]
	v_pk_mul_f32 v[64:65], v[64:65], v[238:239] op_sel_hi:[1,0]
	v_pk_mul_f32 v[66:67], v[66:67], v[238:239] op_sel_hi:[1,0]
	s_waitcnt lgkmcnt(2)
	v_cvt_pk_bf16_f32 v240, v76, v77
	v_cvt_pk_bf16_f32 v241, v78, v79
	v_pk_mul_f32 v[88:89], v[76:77], v[220:221]
	v_pk_mul_f32 v[90:91], v[78:79], v[222:223]
	v_cvt_pk_bf16_f32 v244, v88, v89
	v_cvt_pk_bf16_f32 v245, v90, v91
	v_pk_mul_f32 v[84:85], v[84:85], v[224:225]
	v_pk_mul_f32 v[86:87], v[86:87], v[226:227]
	s_waitcnt lgkmcnt(0)
; __device__ __forceinline__ void phase_gdn2(Frame& F, bool ctx_out, bool dry = false) {
;     ...
; #pragma unroll
;                 for (int I = 0; I < 4; ++I) {
;                     f32x4 vn = U[I], oa = (f32x4){0.f, 0.f, 0.f, 0.f};
; #pragma unroll
;                     for (int ks = 0; ks < 4; ++ks) {
;                         const v4u sb4 = (v4u){pk2(S[2 * ks].x, S[2 * ks].y), pk2(S[2 * ks].z, S[2 * ks].w), pk2(S[2 * ks + 1].x, S[2 * ks + 1].y), pk2(S[2 * ks + 1].z, S[2 * ks + 1].w)};
;                         const hb8 fb = __builtin_bit_cast(hb8, sb4);
;                         const v2u w0 = *(const LAS v2u*)(W + (I * 16 + l15) * GS + ks * 32 + q4 * 4), w1 = *(const LAS v2u*)(W + (I * 16 + l15) * GS + ks * 32 + 16 + q4 * 4);
;                         const v2u q0 = *(const LAS v2u*)(QC + (I * 16 + l15) * GS + ks * 32 + q4 * 4), q1 = *(const LAS v2u*)(QC + (I * 16 + l15) * GS + ks * 32 + 16 + q4 * 4);
;                         const v4u fw4 = (v4u){w0.x, w0.y, w1.x, w1.y}, fq4 = (v4u){q0.x, q0.y, q1.x, q1.y};
;                         vn = MFMA16(__builtin_bit_cast(hb8, fw4), fb, vn); oa = MFMA16(__builtin_bit_cast(hb8, fq4), fb, oa); }
;                     const f32x4 ck = *(const LAS f32x4*)(s_ckd + I * 16 + q4 * 4), eg = *(const LAS f32x4*)(s_eG + I * 16 + q4 * 4), rqv = *(const LAS f32x4*)(s_rq + I * 16 + q4 * 4);
;                     const v4u vn4 = (v4u){pk2(vn.x, vn.y), pk2(vn.z, vn.w), 0u, 0u}, vp4 = (v4u){pk2(vn.x * ck.x, vn.y * ck.y), pk2(vn.z * ck.z, vn.w * ck.w), 0u, 0u};
;                     oa = oa * eg;
;                     { const v2u a0 = *(const LAS v2u*)(QKB + (I * 16 + l15) * GB + q4 * 4); const v4u fa4 = (v4u){a0.x, a0.y, 0u, 0u}; oa = MFMA16(__builtin_bit_cast(hb8, fa4), __builtin_bit_cast(hb8, vn4), oa); }
;                     oa = oa * rqv;
; #pragma unroll
;                     for (int i = 0; i < 4; ++i) O16[(I * 16 + q4 * 4 + i) * GS + vb * 16 + l15] = (bf16)f2bf(oa[i]);
;                     const float ege = s_eGend[I];
;                     const hb8 fbn = __builtin_bit_cast(hb8, vp4);
; #pragma unroll
;                     for (int kt = 0; kt < 8; ++kt) { const v2u a0 = *(const LAS v2u*)(KCT + (kt * 16 + l15) * GT + I * 16 + q4 * 4); const v4u fa4 = (v4u){a0.x, a0.y, 0u, 0u}; S[kt] = MFMA16(__builtin_bit_cast(hb8, fa4), fbn, S[kt] * ege); }
;                 }
;                 LDS_BARRIER();
	v_mfma_f32_16x16x32_bf16 v[36:39], v[202:205], v[244:247], v[36:39]
	v_mfma_f32_16x16x32_bf16 v[40:43], v[204:207], v[244:247], v[40:43]
	v_mfma_f32_16x16x32_bf16 v[84:87], v[232:235], v[240:243], v[84:87]
	v_add_u32_e32 v250, 13056, v0
	v_mfma_f32_16x16x32_bf16 v[44:47], v[206:209], v[244:247], v[44:47]
	v_mfma_f32_16x16x32_bf16 v[48:51], v[208:211], v[244:247], v[48:51]
	v_mfma_f32_16x16x32_bf16 v[52:55], v[210:213], v[244:247], v[52:55]
	v_mfma_f32_16x16x32_bf16 v[56:59], v[212:215], v[244:247], v[56:59]
	v_mfma_f32_16x16x32_bf16 v[60:63], v[214:217], v[244:247], v[60:63]
	v_mfma_f32_16x16x32_bf16 v[64:67], v[216:219], v[244:247], v[64:67]
	ds_read_b64 v[154:155], v250
	ds_read_b64 v[156:157], v250 offset:32
	ds_read_b64 v[170:171], v250 offset:17408
	ds_read_b64 v[172:173], v250 offset:17440
	ds_read_b64 v[158:159], v250 offset:64
	ds_read_b64 v[160:161], v250 offset:96
	ds_read_b64 v[174:175], v250 offset:17472
	ds_read_b64 v[176:177], v250 offset:17504
	v_pk_mul_f32 v[84:85], v[84:85], v[228:229]
	v_pk_mul_f32 v[86:87], v[86:87], v[230:231]
	v_cvt_pk_bf16_f32 v88, v84, v85
	v_cvt_pk_bf16_f32 v90, v86, v87
	v_lshrrev_b32_e32 v89, 16, v88
	v_lshrrev_b32_e32 v91, 16, v90
	ds_write_b16 v253, v88 offset:8704
	ds_write_b16 v253, v89 offset:8976
	ds_write_b16 v253, v90 offset:9248
	ds_write_b16 v253, v91 offset:9520
	v_cvt_pk_bf16_f32 v186, v36, v37
	v_cvt_pk_bf16_f32 v187, v38, v39
	v_cvt_pk_bf16_f32 v188, v40, v41
	v_cvt_pk_bf16_f32 v189, v42, v43
	s_waitcnt lgkmcnt(8)
	ds_read_b64 v[162:163], v250 offset:128
	ds_read_b64 v[164:165], v250 offset:160
	ds_read_b64 v[178:179], v250 offset:17536
	ds_read_b64 v[180:181], v250 offset:17568
	s_waitcnt lgkmcnt(8)
	v_mfma_f32_16x16x32_bf16 v[72:75], v[154:157], v[186:189], v[72:75]
	v_mfma_f32_16x16x32_bf16 v[84:87], v[170:173], v[186:189], 0
	v_cvt_pk_bf16_f32 v190, v44, v45
	v_cvt_pk_bf16_f32 v191, v46, v47
	v_cvt_pk_bf16_f32 v192, v48, v49
	v_cvt_pk_bf16_f32 v193, v50, v51
	ds_read_b64 v[166:167], v250 offset:192
	ds_read_b64 v[168:169], v250 offset:224
	ds_read_b64 v[182:183], v250 offset:17600
	ds_read_b64 v[184:185], v250 offset:17632
	s_waitcnt lgkmcnt(8)
	v_mfma_f32_16x16x32_bf16 v[72:75], v[158:161], v[190:193], v[72:75]
	v_mfma_f32_16x16x32_bf16 v[84:87], v[174:177], v[190:193], v[84:87]
	v_cvt_pk_bf16_f32 v194, v52, v53
	v_cvt_pk_bf16_f32 v195, v54, v55
	v_cvt_pk_bf16_f32 v196, v56, v57
	v_cvt_pk_bf16_f32 v197, v58, v59
	ds_read_b64 v[202:203], v103 offset:34912
	ds_read_b64 v[204:205], v104 offset:34912
	ds_read_b64 v[206:207], v104 offset:37472
	ds_read_b64 v[208:209], v104 offset:40032
	s_waitcnt lgkmcnt(8)
	v_mfma_f32_16x16x32_bf16 v[72:75], v[162:165], v[194:197], v[72:75]
	v_mfma_f32_16x16x32_bf16 v[84:87], v[178:181], v[194:197], v[84:87]
	v_cvt_pk_bf16_f32 v198, v60, v61
	v_cvt_pk_bf16_f32 v199, v62, v63
	v_cvt_pk_bf16_f32 v200, v64, v65
	v_cvt_pk_bf16_f32 v201, v66, v67
	ds_read_b64 v[210:211], v103 offset:45152
	ds_read_b64 v[212:213], v103 offset:47712
	ds_read_b64 v[214:215], v103 offset:50272
	ds_read_b64 v[216:217], v103 offset:52832
	s_waitcnt lgkmcnt(8)
	v_mfma_f32_16x16x32_bf16 v[72:75], v[166:169], v[198:201], v[72:75]
	v_mfma_f32_16x16x32_bf16 v[84:87], v[182:185], v[198:201], v[84:87]
	ds_read_b128 v[220:223], v106 offset:192
	ds_read_b128 v[224:227], v107 offset:704
	ds_read_b128 v[228:231], v102 offset:192
	ds_read_b64 v[232:233], v252 offset:3840
	v_pk_mul_f32 v[36:37], v[36:37], v[238:239] op_sel:[0,1]
	v_pk_mul_f32 v[38:39], v[38:39], v[238:239] op_sel:[0,1]
	v_pk_mul_f32 v[40:41], v[40:41], v[238:239] op_sel:[0,1]
	v_pk_mul_f32 v[42:43], v[42:43], v[238:239] op_sel:[0,1]
	v_pk_mul_f32 v[44:45], v[44:45], v[238:239] op_sel:[0,1]
	v_pk_mul_f32 v[46:47], v[46:47], v[238:239] op_sel:[0,1]
	v_pk_mul_f32 v[48:49], v[48:49], v[238:239] op_sel:[0,1]
	v_pk_mul_f32 v[50:51], v[50:51], v[238:239] op_sel:[0,1]
	v_pk_mul_f32 v[52:53], v[52:53], v[238:239] op_sel:[0,1]
	v_pk_mul_f32 v[54:55], v[54:55], v[238:239] op_sel:[0,1]
	v_pk_mul_f32 v[56:57], v[56:57], v[238:239] op_sel:[0,1]
	v_pk_mul_f32 v[58:59], v[58:59], v[238:239] op_sel:[0,1]
	v_pk_mul_f32 v[60:61], v[60:61], v[238:239] op_sel:[0,1]
	v_pk_mul_f32 v[62:63], v[62:63], v[238:239] op_sel:[0,1]
	v_pk_mul_f32 v[64:65], v[64:65], v[238:239] op_sel:[0,1]
	v_pk_mul_f32 v[66:67], v[66:67], v[238:239] op_sel:[0,1]
	s_waitcnt lgkmcnt(2)
	v_cvt_pk_bf16_f32 v240, v72, v73
	v_cvt_pk_bf16_f32 v241, v74, v75
	v_pk_mul_f32 v[88:89], v[72:73], v[220:221]
	v_pk_mul_f32 v[90:91], v[74:75], v[222:223]
	v_cvt_pk_bf16_f32 v244, v88, v89
	v_cvt_pk_bf16_f32 v245, v90, v91
	v_pk_mul_f32 v[84:85], v[84:85], v[224:225]
	v_pk_mul_f32 v[86:87], v[86:87], v[226:227]
	s_waitcnt lgkmcnt(0)
	v_mfma_f32_16x16x32_bf16 v[36:39], v[202:205], v[244:247], v[36:39]
	v_mfma_f32_16x16x32_bf16 v[40:43], v[204:207], v[244:247], v[40:43]
	v_mfma_f32_16x16x32_bf16 v[84:87], v[232:235], v[240:243], v[84:87]
	v_mfma_f32_16x16x32_bf16 v[44:47], v[206:209], v[244:247], v[44:47]
	v_mfma_f32_16x16x32_bf16 v[48:51], v[208:211], v[244:247], v[48:51]
	v_mfma_f32_16x16x32_bf16 v[52:55], v[210:213], v[244:247], v[52:55]
	v_mfma_f32_16x16x32_bf16 v[56:59], v[212:215], v[244:247], v[56:59]
	v_mfma_f32_16x16x32_bf16 v[60:63], v[214:217], v[244:247], v[60:63]
	v_mfma_f32_16x16x32_bf16 v[64:67], v[216:219], v[244:247], v[64:67]
	s_nop 1
	v_pk_mul_f32 v[84:85], v[84:85], v[228:229]
	v_pk_mul_f32 v[86:87], v[86:87], v[230:231]
	v_cvt_pk_bf16_f32 v88, v84, v85
	v_cvt_pk_bf16_f32 v90, v86, v87
	v_lshrrev_b32_e32 v89, 16, v88
	v_lshrrev_b32_e32 v91, 16, v90
	ds_write_b16 v253, v88 offset:13056
	ds_write_b16 v253, v89 offset:13328
	ds_write_b16 v253, v90 offset:13600
	ds_write_b16 v253, v91 offset:13872
	s_waitcnt lgkmcnt(0)
	s_barrier
	s_waitcnt lgkmcnt(0)
	s_cbranch_scc1 .LBB0_1021

.LBB0_988:
	s_mov_b64 s[30:31], 0
	s_andn2_b64 vcc, exec, s[0:1]
	s_cbranch_vccnz .LBB0_995
	s_waitcnt vmcnt(0)
	v_mul_lo_u32 v1, v145, s44
	s_add_i32 s80, 0, 0x1b000
	v_add3_u32 v1, s80, v1, v142
	ds_read_b128 v[104:107], v1
	ds_read_b128 v[100:103], v1 offset:16
	v_add_u32_e32 v0, s78, v145
	v_cndmask_b32_e64 v0, v146, v0, s[28:29]
	v_add_u32_e32 v117, s77, v0
	s_and_b64 vcc, exec, s[24:25]
	s_cbranch_vccz .LBB0_1012
	s_mov_b64 s[50:51], 0
	s_and_b64 vcc, exec, s[12:13]
	s_cbranch_vccz .LBB0_1004
	v_mul_lo_u32 v0, v117, s11
	v_or_b32_e32 v0, v0, v144
	v_lshlrev_b32_e32 v164, 1, v0
	s_waitcnt lgkmcnt(0)
	v_and_b32_e32 v0, 0xffff0000, v101
	v_lshlrev_b32_e32 v1, 16, v101
	s_waitcnt vmcnt(7)
	v_and_b32_e32 v108, 0xffff0000, v77
	v_lshlrev_b32_e32 v109, 16, v77
	v_lshlrev_b32_e32 v194, 16, v104
	v_and_b32_e32 v195, 0xffff0000, v104
	s_waitcnt vmcnt(6)
	v_lshlrev_b32_e32 v196, 16, v80
	v_and_b32_e32 v197, 0xffff0000, v80
	v_pk_add_f32 v[166:167], v[108:109], v[0:1]
	v_and_b32_e32 v0, 0xffff0000, v102
	v_lshlrev_b32_e32 v1, 16, v102
	v_and_b32_e32 v108, 0xffff0000, v78
	v_lshlrev_b32_e32 v109, 16, v78
	v_lshlrev_b32_e32 v188, 16, v105
	v_and_b32_e32 v189, 0xffff0000, v105
	v_lshlrev_b32_e32 v190, 16, v81
	v_and_b32_e32 v191, 0xffff0000, v81
	v_pk_add_f32 v[194:195], v[196:197], v[194:195]
	v_mov_b32_e32 v165, v2
	v_pk_add_f32 v[170:171], v[108:109], v[0:1]
	v_and_b32_e32 v0, 0xffff0000, v103
	v_lshlrev_b32_e32 v1, 16, v103
	v_and_b32_e32 v108, 0xffff0000, v79
	v_lshlrev_b32_e32 v109, 16, v79
	v_pk_add_f32 v[188:189], v[190:191], v[188:189]
	v_pk_mul_f32 v[196:197], v[194:195], v[194:195]
	v_pk_add_f32 v[174:175], v[108:109], v[0:1]
	v_lshl_add_u64 v[0:1], s[22:23], 0, v[164:165]
	v_lshlrev_b32_e32 v182, 16, v106
	v_and_b32_e32 v183, 0xffff0000, v106
	v_lshlrev_b32_e32 v184, 16, v82
	v_and_b32_e32 v185, 0xffff0000, v82
	v_pk_mul_f32 v[190:191], v[188:189], v[188:189]
	v_add_f32_e32 v165, v196, v197
	v_pk_add_f32 v[182:183], v[184:185], v[182:183]
	v_add_f32_e32 v165, v190, v165
	v_lshlrev_b32_e32 v178, 16, v107
	v_and_b32_e32 v179, 0xffff0000, v107
	v_lshlrev_b32_e32 v180, 16, v83
	v_and_b32_e32 v181, 0xffff0000, v83
	v_pk_mul_f32 v[184:185], v[182:183], v[182:183]
	v_add_f32_e32 v165, v191, v165
	v_pk_add_f32 v[178:179], v[180:181], v[178:179]
	v_add_f32_e32 v165, v184, v165
	v_pk_mul_f32 v[180:181], v[178:179], v[178:179]
	v_lshlrev_b32_e32 v200, 16, v100
	v_and_b32_e32 v201, 0xffff0000, v100
	v_lshlrev_b32_e32 v202, 16, v76
	v_and_b32_e32 v203, 0xffff0000, v76
	v_add_f32_e32 v165, v185, v165
	v_pk_add_f32 v[200:201], v[202:203], v[200:201]
	v_add_f32_e32 v165, v180, v165
	v_pk_mul_f32 v[202:203], v[200:201], v[200:201]
	v_add_f32_e32 v165, v181, v165
	v_add_f32_e32 v165, v202, v165
	v_pk_mul_f32 v[168:169], v[166:167], v[166:167]
	v_add_f32_e32 v165, v203, v165
	v_add_f32_e32 v165, v169, v165
	v_pk_mul_f32 v[172:173], v[170:171], v[170:171]
	v_add_f32_e32 v165, v168, v165
	v_add_f32_e32 v165, v173, v165
	v_pk_mul_f32 v[176:177], v[174:175], v[174:175]
	v_add_f32_e32 v165, v172, v165
	v_add_f32_e32 v165, v177, v165
	v_add_f32_e32 v165, v176, v165
	v_lshl_add_u32 v108, v144, 2, 0
	v_add_u32_e32 v160, 0x25000, v108
	v_add_f32_dpp v165, v165, v165 quad_perm:[1,0,3,2] row_mask:0xf bank_mask:0xf bound_ctrl:1
	ds_read_b128 v[108:111], v160
	ds_read_b128 v[152:155], v160 offset:16
	ds_read_b128 v[156:159], v160 offset:32
	ds_read_b128 v[160:163], v160 offset:48
	v_add_f32_dpp v165, v165, v165 quad_perm:[2,3,0,1] row_mask:0xf bank_mask:0xf bound_ctrl:1
	s_waitcnt vmcnt(4)
	v_lshlrev_b32_e32 v186, 16, v74
	v_and_b32_e32 v187, 0xffff0000, v74
	v_add_f32_dpp v165, v165, v165 row_half_mirror row_mask:0xf bank_mask:0xf bound_ctrl:1
	v_fmamk_f32 v165, v165, 0x3c000000, v126
	v_rsq_f32_e32 v168, v165
	v_lshlrev_b32_e32 v192, 16, v73
	v_and_b32_e32 v193, 0xffff0000, v73
	v_lshlrev_b32_e32 v198, 16, v72
	v_pk_mul_f32 v[176:177], v[194:195], v[168:169] op_sel_hi:[1,0]
	v_and_b32_e32 v199, 0xffff0000, v72
	s_waitcnt lgkmcnt(3)
	v_pk_mul_f32 v[108:109], v[108:109], v[176:177]
	v_pk_mul_f32 v[176:177], v[188:189], v[168:169] op_sel_hi:[1,0]
	v_lshlrev_b32_e32 v172, 16, v75
	v_pk_mul_f32 v[110:111], v[110:111], v[176:177]
	v_pk_mul_f32 v[176:177], v[182:183], v[168:169] op_sel_hi:[1,0]
	v_and_b32_e32 v173, 0xffff0000, v75
	s_waitcnt lgkmcnt(2)
	v_pk_mul_f32 v[152:153], v[152:153], v[176:177]
	v_pk_mul_f32 v[176:177], v[178:179], v[168:169] op_sel_hi:[1,0]
	v_pk_mul_f32 v[108:109], v[108:109], v[198:199]
	v_pk_mul_f32 v[154:155], v[154:155], v[176:177]
	v_pk_mul_f32 v[110:111], v[110:111], v[192:193]
	v_pk_mul_f32 v[152:153], v[152:153], v[186:187]
	v_pk_mul_f32 v[154:155], v[154:155], v[172:173]
	v_cvt_pk_bf16_f32 v108, v108, v109
	v_cvt_pk_bf16_f32 v109, v110, v111
	v_cvt_pk_bf16_f32 v110, v152, v153
	v_cvt_pk_bf16_f32 v111, v154, v155
	global_store_dwordx4 v164, v[108:111], s[22:23]
	v_lshlrev_b32_e32 v152, 16, v69
	v_and_b32_e32 v153, 0xffff0000, v69
	v_pk_mul_f32 v[108:109], v[200:201], v[168:169] op_sel_hi:[1,0]
	v_lshlrev_b32_e32 v110, 16, v68
	s_waitcnt lgkmcnt(1)
	v_pk_mul_f32 v[108:109], v[156:157], v[108:109]
	v_and_b32_e32 v111, 0xffff0000, v68
	v_pk_mul_f32 v[108:109], v[108:109], v[110:111]
	v_pk_mul_f32 v[110:111], v[166:167], v[168:169] op_sel_hi:[1,0]
	v_lshlrev_b32_e32 v154, 16, v70
	v_pk_mul_f32 v[110:111], v[158:159], v[110:111] op_sel:[0,1] op_sel_hi:[1,0]
	v_and_b32_e32 v155, 0xffff0000, v70
	v_pk_mul_f32 v[110:111], v[110:111], v[152:153]
	v_pk_mul_f32 v[152:153], v[170:171], v[168:169] op_sel_hi:[1,0]
	v_lshlrev_b32_e32 v156, 16, v71
	s_waitcnt lgkmcnt(0)
	v_pk_mul_f32 v[152:153], v[152:153], v[160:161] op_sel:[1,0] op_sel_hi:[0,1]
	v_pk_mul_f32 v[152:153], v[152:153], v[154:155]
	v_pk_mul_f32 v[154:155], v[174:175], v[168:169] op_sel_hi:[1,0]
	v_and_b32_e32 v157, 0xffff0000, v71
	v_pk_mul_f32 v[154:155], v[154:155], v[162:163] op_sel:[1,0] op_sel_hi:[0,1]
	v_pk_mul_f32 v[154:155], v[154:155], v[156:157]
	v_cvt_pk_bf16_f32 v108, v108, v109
	v_cvt_pk_bf16_f32 v109, v110, v111
	v_cvt_pk_bf16_f32 v110, v152, v153
	v_cvt_pk_bf16_f32 v111, v154, v155
	s_mov_b64 s[52:53], -1
	s_and_b64 vcc, exec, s[50:51]
	s_cbranch_vccz .LBB0_1013
	s_branch .LBB0_1005

.LBB0_1015:
	v_add_u32_e32 v0, s58, v147
	v_sub_u32_e32 v1, s79, v0
	s_waitcnt lgkmcnt(0)
	v_add_u32_e32 v100, s78, v0
	v_mul_lo_u32 v0, v0, s44
	v_add3_u32 v0, s80, v0, v142
	v_cndmask_b32_e64 v1, v1, v100, s[28:29]
	ds_read_b128 v[104:107], v0
	ds_read_b128 v[100:103], v0 offset:16
	v_add_u32_e32 v108, s77, v1
	s_and_b64 vcc, exec, s[24:25]
	s_cbranch_vccz .LBB0_1018
	s_mov_b64 s[50:51], 0
	s_and_b64 vcc, exec, s[12:13]
	s_mov_b64 s[52:53], 0
	s_cbranch_vccz .LBB0_1019
	s_waitcnt lgkmcnt(1)
	v_lshlrev_b32_e32 v190, 16, v104
	v_and_b32_e32 v191, 0xffff0000, v104
	s_nop 0
	v_lshlrev_b32_e32 v192, 16, v96
	v_and_b32_e32 v193, 0xffff0000, v96
	v_lshlrev_b32_e32 v184, 16, v105
	v_and_b32_e32 v185, 0xffff0000, v105
	v_lshlrev_b32_e32 v186, 16, v97
	v_and_b32_e32 v187, 0xffff0000, v97
	v_pk_add_f32 v[96:97], v[192:193], v[190:191]
	v_pk_add_f32 v[184:185], v[186:187], v[184:185]
	v_pk_mul_f32 v[190:191], v[96:97], v[96:97]
	v_lshlrev_b32_e32 v180, 16, v106
	v_and_b32_e32 v181, 0xffff0000, v106
	v_lshlrev_b32_e32 v182, 16, v98
	v_and_b32_e32 v183, 0xffff0000, v98
	v_pk_mul_f32 v[186:187], v[184:185], v[184:185]
	s_nop 0
	v_lshlrev_b32_e32 v188, 16, v89
	v_and_b32_e32 v189, 0xffff0000, v89
	v_add_f32_e32 v89, v190, v191
	v_mul_lo_u32 v0, v108, s11
	v_lshlrev_b32_e32 v178, 16, v99
	v_and_b32_e32 v179, 0xffff0000, v99
	v_pk_add_f32 v[98:99], v[182:183], v[180:181]
	v_add_f32_e32 v89, v186, v89
	v_or_b32_e32 v0, v0, v144
	v_lshlrev_b32_e32 v176, 16, v107
	v_and_b32_e32 v177, 0xffff0000, v107
	v_pk_mul_f32 v[180:181], v[98:99], v[98:99]
	v_add_f32_e32 v89, v187, v89
	v_lshlrev_b32_e32 v110, 1, v0
	s_waitcnt lgkmcnt(0)
	v_and_b32_e32 v0, 0xffff0000, v101
	v_lshlrev_b32_e32 v1, 16, v101
	v_and_b32_e32 v152, 0xffff0000, v93
	v_lshlrev_b32_e32 v153, 16, v93
	v_lshl_add_u32 v93, v144, 2, 0
	v_pk_add_f32 v[176:177], v[178:179], v[176:177]
	v_add_f32_e32 v89, v180, v89
	v_pk_add_f32 v[168:169], v[152:153], v[0:1]
	v_and_b32_e32 v0, 0xffff0000, v102
	v_lshlrev_b32_e32 v1, 16, v102
	v_and_b32_e32 v152, 0xffff0000, v94
	v_lshlrev_b32_e32 v153, 16, v94
	v_add_u32_e32 v93, 0x25000, v93
	v_pk_mul_f32 v[178:179], v[176:177], v[176:177]
	v_lshlrev_b32_e32 v194, 16, v100
	v_and_b32_e32 v195, 0xffff0000, v100
	v_lshlrev_b32_e32 v100, 16, v92
	v_and_b32_e32 v101, 0xffff0000, v92
	v_add_f32_e32 v89, v181, v89
	v_pk_add_f32 v[172:173], v[152:153], v[0:1]
	ds_read_b128 v[152:155], v93
	ds_read_b128 v[156:159], v93 offset:16
	ds_read_b128 v[160:163], v93 offset:32
	ds_read_b128 v[164:167], v93 offset:48
	v_pk_add_f32 v[92:93], v[100:101], v[194:195]
	v_add_f32_e32 v89, v178, v89
	v_pk_mul_f32 v[100:101], v[92:93], v[92:93]
	v_add_f32_e32 v89, v179, v89
	v_add_f32_e32 v89, v100, v89
	v_pk_mul_f32 v[170:171], v[168:169], v[168:169]
	v_add_f32_e32 v89, v101, v89
	v_add_f32_e32 v89, v171, v89
	v_pk_mul_f32 v[174:175], v[172:173], v[172:173]
	v_and_b32_e32 v0, 0xffff0000, v103
	v_lshlrev_b32_e32 v1, 16, v103
	v_and_b32_e32 v94, 0xffff0000, v95
	v_lshlrev_b32_e32 v95, 16, v95
	v_add_f32_e32 v89, v170, v89
	v_pk_add_f32 v[94:95], v[94:95], v[0:1]
	v_add_f32_e32 v89, v175, v89
	v_pk_mul_f32 v[102:103], v[94:95], v[94:95]
	v_add_f32_e32 v89, v174, v89
	v_add_f32_e32 v89, v103, v89
	v_add_f32_e32 v89, v102, v89
	v_lshlrev_b32_e32 v182, 16, v90
	v_and_b32_e32 v183, 0xffff0000, v90
	v_add_f32_dpp v89, v89, v89 quad_perm:[1,0,3,2] row_mask:0xf bank_mask:0xf bound_ctrl:1
	v_lshlrev_b32_e32 v192, 16, v88
	v_and_b32_e32 v193, 0xffff0000, v88
	v_add_f32_dpp v89, v89, v89 quad_perm:[2,3,0,1] row_mask:0xf bank_mask:0xf bound_ctrl:1
	v_lshlrev_b32_e32 v88, 16, v91
	v_mov_b32_e32 v111, v2
	v_add_f32_dpp v89, v89, v89 row_half_mirror row_mask:0xf bank_mask:0xf bound_ctrl:1
	v_fmamk_f32 v89, v89, 0x3c000000, v126
	v_rsq_f32_e32 v100, v89
	v_and_b32_e32 v89, 0xffff0000, v91
	v_lshl_add_u64 v[0:1], s[22:23], 0, v[110:111]
	s_mov_b64 s[52:53], -1
	v_pk_mul_f32 v[90:91], v[96:97], v[100:101] op_sel_hi:[1,0]
	v_pk_mul_f32 v[96:97], v[184:185], v[100:101] op_sel_hi:[1,0]
	v_pk_mul_f32 v[98:99], v[98:99], v[100:101] op_sel_hi:[1,0]
	v_pk_mul_f32 v[102:103], v[176:177], v[100:101] op_sel_hi:[1,0]
	s_waitcnt lgkmcnt(3)
	v_pk_mul_f32 v[90:91], v[152:153], v[90:91]
	v_pk_mul_f32 v[96:97], v[154:155], v[96:97]
	s_waitcnt lgkmcnt(2)
	v_pk_mul_f32 v[98:99], v[156:157], v[98:99]
	v_pk_mul_f32 v[102:103], v[158:159], v[102:103]
	v_pk_mul_f32 v[90:91], v[90:91], v[192:193]
	v_pk_mul_f32 v[96:97], v[96:97], v[188:189]
	v_pk_mul_f32 v[98:99], v[98:99], v[182:183]
	v_pk_mul_f32 v[102:103], v[102:103], v[88:89]
	v_cvt_pk_bf16_f32 v88, v90, v91
	v_cvt_pk_bf16_f32 v89, v96, v97
	v_cvt_pk_bf16_f32 v90, v98, v99
	v_cvt_pk_bf16_f32 v91, v102, v103
	global_store_dwordx4 v110, v[88:91], s[22:23]
	s_nop 1
	v_pk_mul_f32 v[88:89], v[92:93], v[100:101] op_sel_hi:[1,0]
	v_lshlrev_b32_e32 v90, 16, v84
	s_waitcnt lgkmcnt(1)
	v_pk_mul_f32 v[88:89], v[160:161], v[88:89]
	v_and_b32_e32 v91, 0xffff0000, v84
	v_pk_mul_f32 v[88:89], v[88:89], v[90:91]
	v_pk_mul_f32 v[90:91], v[168:169], v[100:101] op_sel_hi:[1,0]
	v_lshlrev_b32_e32 v84, 16, v85
	v_pk_mul_f32 v[90:91], v[162:163], v[90:91] op_sel:[0,1] op_sel_hi:[1,0]
	v_and_b32_e32 v85, 0xffff0000, v85
	v_pk_mul_f32 v[84:85], v[90:91], v[84:85]
	v_pk_mul_f32 v[90:91], v[172:173], v[100:101] op_sel_hi:[1,0]
	v_lshlrev_b32_e32 v92, 16, v86
	s_waitcnt lgkmcnt(0)
	v_pk_mul_f32 v[90:91], v[90:91], v[164:165] op_sel:[1,0] op_sel_hi:[0,1]
	v_and_b32_e32 v93, 0xffff0000, v86
	v_pk_mul_f32 v[90:91], v[90:91], v[92:93]
	v_pk_mul_f32 v[92:93], v[94:95], v[100:101] op_sel_hi:[1,0]
	v_lshlrev_b32_e32 v86, 16, v87
	v_pk_mul_f32 v[92:93], v[92:93], v[166:167] op_sel:[1,0] op_sel_hi:[0,1]
	v_and_b32_e32 v87, 0xffff0000, v87
	v_pk_mul_f32 v[86:87], v[92:93], v[86:87]
	v_cvt_pk_bf16_f32 v100, v88, v89
	v_cvt_pk_bf16_f32 v101, v84, v85
	v_cvt_pk_bf16_f32 v102, v90, v91
	v_cvt_pk_bf16_f32 v103, v86, v87
	s_branch .LBB0_1019

.LBB0_1019:
	s_and_b64 vcc, exec, s[50:51]
	s_cbranch_vccz .LBB0_995
	s_nop 0
	v_lshl_or_b32 v84, v108, 13, v142
	v_mov_b32_e32 v85, v2
	v_lshl_add_u64 v[0:1], s[20:21], 0, v[84:85]
	s_waitcnt lgkmcnt(1)
	global_store_dwordx4 v84, v[104:107], s[20:21]
	s_mov_b64 s[52:53], -1
	s_branch .LBB0_995
